# helper priority raised only after the y flush (flush at normal priority)
# speedup vs baseline: 1.0026x; 1.0026x over previous
.Lmy_f_hl2:
	s_setprio 3
	s_bfe_u32 s100, s62, 0x20006
	s_lshl_b32 s100, s100, 2
	s_add_i32 s101, s100, -16
	s_add_i32 s100, s100, -12
	s_cmp_lg_u32 s65, 0
	s_cbranch_scc1 .Lmy_f_nol2
	v_add_u32_e32 v70, s101, v70
	v_subrev_u32_e32 v71, s101, v71
	v_add_u32_e32 v21, 64, v70
	v_subrev_u32_e32 v26, 64, v71
	v_cndmask_b32_e64 v32, v26, v21, s[4:5]
	v_ashrrev_i32_e32 v33, 31, v32
	v_lshl_add_u64 v[44:45], v[32:33], 0, s[40:41]
	v_mad_u64_u32 v[46:47], s[96:97], v44, s56, v[50:51]
	v_mad_i32_i24 v47, v45, s56, v47
	v_mov_b32_e32 v166, v46
	v_mov_b32_e32 v167, v47
	global_load_dwordx2 v[26:27], v[46:47], off
	v_mov_b32_e32 v30, v20
	v_mov_b32_e32 v31, v20
	v_cmp_lt_i32_e64 s[96:97], 0, v32
	v_mov_b64_e32 v[28:29], v[30:31]
	s_and_saveexec_b64 s[24:25], s[96:97]
	s_cbranch_execz .Lmy_f_k659
	v_add_co_u32_e32 v28, vcc, 0xfffff000, v46
	s_nop 1
	v_addc_co_u32_e32 v29, vcc, -1, v47, vcc
	global_load_dwordx2 v[28:29], v[28:29], off offset:-2048
